# V pass cross-lane reduce: levels 32 and 16 via v_permlane32_swap / v_permlane16_swap (24 cndmask + 12 ds_bpermute per step replaced by 12 swaps), bit-identical sums
# speedup vs baseline: 1.0108x; 1.0108x over previous
.Lvx_skip:
	v_pk_fma_f32 v[86:87], v[128:129], v[86:87], v[94:95] op_sel_hi:[0,1,1]
	v_pk_fma_f32 v[90:91], v[128:129], v[90:91], v[98:99] op_sel_hi:[0,1,1]
	v_pk_fma_f32 v[94:95], v[128:129], v[96:97], v[100:101] op_sel_hi:[0,1,1]
	v_pk_fma_f32 v[76:77], v[128:129], v[76:77], v[80:81] op_sel_hi:[0,1,1]
	v_cvt_pk_f32_fp8_e32 v[80:81], v78
	v_cvt_pk_f32_fp8_sdwa v[96:97], v78 src0_sel:WORD_1
	v_cvt_pk_f32_fp8_e32 v[98:99], v79
	v_cvt_pk_f32_fp8_sdwa v[78:79], v79 src0_sel:WORD_1
	v_pk_fma_f32 v[80:81], v[128:129], v[80:81], v[84:85] op_sel_hi:[0,1,1]
	v_pk_fma_f32 v[84:85], v[128:129], v[96:97], v[88:89] op_sel_hi:[0,1,1]
	v_pk_fma_f32 v[88:89], v[128:129], v[98:99], v[92:93] op_sel_hi:[0,1,1]
	v_pk_fma_f32 v[78:79], v[128:129], v[78:79], v[82:83] op_sel_hi:[0,1,1]
	v_cvt_pk_f32_fp8_e32 v[82:83], v72
	v_cvt_pk_f32_fp8_sdwa v[92:93], v72 src0_sel:WORD_1
	v_cvt_pk_f32_fp8_e32 v[96:97], v73
	v_cvt_pk_f32_fp8_sdwa v[72:73], v73 src0_sel:WORD_1
	v_pk_fma_f32 v[82:83], v[128:129], v[82:83], v[86:87] op_sel:[1,0,0]
	v_pk_fma_f32 v[86:87], v[128:129], v[92:93], v[90:91] op_sel:[1,0,0]
	v_pk_fma_f32 v[90:91], v[128:129], v[96:97], v[94:95] op_sel:[1,0,0]
	v_pk_fma_f32 v[72:73], v[128:129], v[72:73], v[76:77] op_sel:[1,0,0]
	v_cvt_pk_f32_fp8_e32 v[76:77], v74
	v_cvt_pk_f32_fp8_sdwa v[92:93], v74 src0_sel:WORD_1
	v_cvt_pk_f32_fp8_e32 v[94:95], v75
	v_cvt_pk_f32_fp8_sdwa v[74:75], v75 src0_sel:WORD_1
	v_pk_fma_f32 v[76:77], v[128:129], v[76:77], v[80:81] op_sel:[1,0,0]
	v_pk_fma_f32 v[80:81], v[128:129], v[92:93], v[84:85] op_sel:[1,0,0]
	v_pk_fma_f32 v[84:85], v[128:129], v[94:95], v[88:89] op_sel:[1,0,0]
	v_pk_fma_f32 v[74:75], v[128:129], v[74:75], v[78:79] op_sel:[1,0,0]
	v_cvt_pk_f32_fp8_e32 v[78:79], v68
	v_cvt_pk_f32_fp8_sdwa v[88:89], v68 src0_sel:WORD_1
	v_cvt_pk_f32_fp8_e32 v[92:93], v69
	v_cvt_pk_f32_fp8_sdwa v[68:69], v69 src0_sel:WORD_1
	v_pk_fma_f32 v[78:79], v[130:131], v[78:79], v[82:83] op_sel_hi:[0,1,1]
	v_pk_fma_f32 v[82:83], v[130:131], v[88:89], v[86:87] op_sel_hi:[0,1,1]
	v_pk_fma_f32 v[86:87], v[130:131], v[92:93], v[90:91] op_sel_hi:[0,1,1]
	v_pk_fma_f32 v[68:69], v[130:131], v[68:69], v[72:73] op_sel_hi:[0,1,1]
	v_cvt_pk_f32_fp8_e32 v[72:73], v70
	v_cvt_pk_f32_fp8_sdwa v[88:89], v70 src0_sel:WORD_1
	v_cvt_pk_f32_fp8_e32 v[90:91], v71
	v_cvt_pk_f32_fp8_sdwa v[70:71], v71 src0_sel:WORD_1
	v_pk_fma_f32 v[72:73], v[130:131], v[72:73], v[76:77] op_sel_hi:[0,1,1]
	v_pk_fma_f32 v[76:77], v[130:131], v[88:89], v[80:81] op_sel_hi:[0,1,1]
	v_pk_fma_f32 v[80:81], v[130:131], v[90:91], v[84:85] op_sel_hi:[0,1,1]
	v_cvt_pk_f32_fp8_e32 v[84:85], v64
	v_cvt_pk_f32_fp8_sdwa v[88:89], v64 src0_sel:WORD_1
	v_cvt_pk_f32_fp8_e32 v[90:91], v65
	v_cvt_pk_f32_fp8_sdwa v[64:65], v65 src0_sel:WORD_1
	v_pk_fma_f32 v[70:71], v[130:131], v[70:71], v[74:75] op_sel_hi:[0,1,1]
	v_mov_b32_e32 v74, v131
	v_pk_fma_f32 v[78:79], v[74:75], v[84:85], v[78:79] op_sel_hi:[0,1,1]
	v_pk_fma_f32 v[64:65], v[74:75], v[64:65], v[68:69] op_sel_hi:[0,1,1]
	v_cvt_pk_f32_fp8_e32 v[68:69], v66
	v_pk_fma_f32 v[82:83], v[74:75], v[88:89], v[82:83] op_sel_hi:[0,1,1]
	v_pk_fma_f32 v[84:85], v[74:75], v[90:91], v[86:87] op_sel_hi:[0,1,1]
	v_cvt_pk_f32_fp8_sdwa v[86:87], v66 src0_sel:WORD_1
	v_cvt_pk_f32_fp8_e32 v[88:89], v67
	v_cvt_pk_f32_fp8_sdwa v[66:67], v67 src0_sel:WORD_1
	v_pk_fma_f32 v[68:69], v[74:75], v[68:69], v[72:73] op_sel_hi:[0,1,1]
	v_pk_fma_f32 v[72:73], v[74:75], v[86:87], v[76:77] op_sel_hi:[0,1,1]
	v_pk_fma_f32 v[76:77], v[74:75], v[88:89], v[80:81] op_sel_hi:[0,1,1]
	v_pk_fma_f32 v[66:67], v[74:75], v[66:67], v[70:71] op_sel_hi:[0,1,1]
	v_permlane32_swap_b32 v78, v68
	v_permlane32_swap_b32 v79, v69
	v_permlane32_swap_b32 v82, v72
	v_permlane32_swap_b32 v83, v73
	v_permlane32_swap_b32 v84, v76
	v_permlane32_swap_b32 v85, v77
	v_permlane32_swap_b32 v64, v66
	v_permlane32_swap_b32 v65, v67
	v_pk_add_f32 v[68:69], v[78:79], v[68:69]
	v_pk_add_f32 v[70:71], v[82:83], v[72:73]
	v_pk_add_f32 v[72:73], v[84:85], v[76:77]
	v_pk_add_f32 v[64:65], v[64:65], v[66:67]
	s_nop 1
	v_permlane16_swap_b32 v68, v72
	v_permlane16_swap_b32 v69, v73
	v_permlane16_swap_b32 v70, v64
	v_permlane16_swap_b32 v71, v65
	v_pk_add_f32 v[66:67], v[68:69], v[72:73]
	v_pk_add_f32 v[64:65], v[70:71], v[64:65]
	v_and_b32_e32 v89, 0xffff0000, v212
	v_cndmask_b32_e64 v68, v66, v64, s[12:13]
	v_cndmask_b32_e64 v69, v67, v65, s[12:13]
	ds_bpermute_b32 v68, v206, v68
	ds_bpermute_b32 v69, v206, v69
	v_and_b32_e32 v91, 0xffff0000, v213
	v_lshlrev_b32_e32 v88, 16, v212
	v_lshlrev_b32_e32 v90, 16, v213
	v_readlane_b32 s98, v248, s59
	v_readlane_b32 s99, v249, s59
	v_cndmask_b32_e64 v65, v65, v67, s[12:13]
	v_cndmask_b32_e64 v64, v64, v66, s[12:13]
	v_pk_fma_f32 v[66:67], v[88:89], s[74:75], v[90:91] op_sel_hi:[1,0,1]
	v_lshlrev_b64 v[92:93], 13, v[186:187]
	v_pk_add_f32 v[66:67], v[66:67], s[98:99] op_sel_hi:[1,0] neg_lo:[0,1] neg_hi:[0,1]
	v_lshl_add_u64 v[70:71], s[78:79], 0, v[92:93]
	v_pk_mul_f32 v[66:67], s[98:99], v[66:67] op_sel:[1,0]
	s_waitcnt lgkmcnt(0)
	v_pk_add_f32 v[64:65], v[64:65], v[68:69]
	ds_bpermute_b32 v64, v250, v64
	ds_bpermute_b32 v65, v250, v65
	v_pk_fma_f32 v[66:67], v[66:67], v[178:179], v[180:181]
	v_lshl_add_u64 v[70:71], v[70:71], 0, v[138:139]
	s_waitcnt lgkmcnt(0)
	v_pk_fma_f32 v[64:65], v[66:67], s[74:75], v[64:65] op_sel_hi:[1,0,1]
	s_add_i32 s16, s16, 16
	s_addk_i32 s17, 0x100
	s_add_i32 s34, s34, 0x40000
	s_and_b64 vcc, exec, s[0:1]
	s_mov_b32 s0, s61
	global_store_dwordx2 v[70:71], v[64:65], off nt
	s_cbranch_vccnz .LBB0_938
.LBB0_934:
	s_add_i32 s15, s17, 0xffffff80
	s_and_b32 s15, s15, 0x780
	v_lshl_add_u32 v76, s15, 2, v189
	ds_read_b128 v[64:67], v76
	s_add_i32 s14, s34, 0xfffc0000
	s_add_i32 s1, s0, 1
	s_and_b32 s14, s14, 0x1e00000
	s_add_u32 s14, s38, s14
	s_waitcnt lgkmcnt(0)
	s_addc_u32 s15, s39, 0
	ds_read_b128 v[68:71], v76 offset:16
	ds_read_b128 v[72:75], v76 offset:32
	ds_read_b128 v[128:131], v76 offset:48
	v_lshl_or_b32 v65, v65, 7, v137
	v_lshl_or_b32 v64, v64, 7, v174
	global_load_dwordx4 v[124:127], v64, s[14:15]
	global_load_dwordx4 v[120:123], v65, s[14:15]
	v_lshl_or_b32 v64, v67, 7, v137
	v_lshl_or_b32 v65, v66, 7, v174
	global_load_dwordx4 v[116:119], v65, s[14:15]
	global_load_dwordx4 v[112:115], v64, s[14:15]
	s_waitcnt lgkmcnt(2)
	v_lshl_or_b32 v64, v69, 7, v137
	v_lshl_or_b32 v65, v68, 7, v174
	global_load_dwordx4 v[108:111], v65, s[14:15]
	global_load_dwordx4 v[104:107], v64, s[14:15]
	v_lshl_or_b32 v64, v71, 7, v137
	v_lshl_or_b32 v65, v70, 7, v174
	global_load_dwordx4 v[100:103], v65, s[14:15]
	global_load_dwordx4 v[96:99], v64, s[14:15]
	s_waitcnt lgkmcnt(1)
	v_lshl_or_b32 v64, v73, 7, v137
	v_lshl_or_b32 v65, v72, 7, v174
	global_load_dwordx4 v[92:95], v65, s[14:15]
	global_load_dwordx4 v[88:91], v64, s[14:15]
	s_and_b32 s59, s1, 15
	v_lshl_or_b32 v64, v75, 7, v137
	v_lshl_or_b32 v65, v74, 7, v174
	s_add_i32 s1, s16, -16
	v_or_b32_e32 v186, s59, v176
	global_load_dwordx4 v[84:87], v65, s[14:15]
	global_load_dwordx4 v[80:83], v64, s[14:15]
	s_waitcnt lgkmcnt(0)
	s_and_b32 s1, s1, 0x780
	v_ashrrev_i32_e32 v187, 31, v186
	v_lshl_or_b32 v64, v129, 7, v137
	v_lshl_or_b32 v65, v128, 7, v174
	v_or_b32_e32 v214, s1, v192
	global_load_dwordx4 v[76:79], v65, s[14:15]
	global_load_dwordx4 v[72:75], v64, s[14:15]
	v_lshlrev_b32_e32 v64, 7, v131
	v_lshlrev_b32_e32 v65, 7, v130
	v_or_b32_e32 v64, v64, v137
	v_or_b32_e32 v65, v65, v174
	s_and_b32 s1, s0, 14
	s_waitcnt vmcnt(30)
	v_cvt_pk_f32_fp8_e32 v[224:225], v0
	v_cvt_pk_f32_fp8_sdwa v[226:227], v0 src0_sel:WORD_1
	v_cvt_pk_f32_fp8_e32 v[228:229], v1
	v_cvt_pk_f32_fp8_sdwa v[230:231], v1 src0_sel:WORD_1
	global_load_dwordx4 v[68:71], v65, s[14:15]
	s_nop 0
	global_load_dwordx4 v[64:67], v64, s[14:15]
	v_lshl_add_u32 v128, s1, 9, v193
	s_waitcnt vmcnt(31)
	v_cvt_pk_f32_fp8_e32 v[240:241], v4
	v_cvt_pk_f32_fp8_sdwa v[242:243], v4 src0_sel:WORD_1
	v_cvt_pk_f32_fp8_e32 v[244:245], v5
	v_cvt_pk_f32_fp8_sdwa v[246:247], v5 src0_sel:WORD_1
	ds_read_b128 v[216:219], v128
	ds_read_b128 v[220:223], v128 offset:16
	ds_read_b128 v[132:135], v128 offset:32
	ds_read_b128 v[128:131], v128 offset:48
	v_cvt_pk_f32_fp8_e32 v[232:233], v2
	s_waitcnt lgkmcnt(3)
	v_pk_fma_f32 v[224:225], v[216:217], v[224:225], 0 op_sel_hi:[0,1,0]
	v_pk_fma_f32 v[226:227], v[216:217], v[226:227], 0 op_sel_hi:[0,1,0]
	v_pk_fma_f32 v[228:229], v[216:217], v[228:229], 0 op_sel_hi:[0,1,0]
	v_pk_fma_f32 v[230:231], v[216:217], v[230:231], 0 op_sel_hi:[0,1,0]
	v_cvt_pk_f32_fp8_sdwa v[234:235], v2 src0_sel:WORD_1
	v_cvt_pk_f32_fp8_e32 v[236:237], v3
	v_cvt_pk_f32_fp8_sdwa v[238:239], v3 src0_sel:WORD_1
	v_pk_fma_f32 v[224:225], v[216:217], v[240:241], v[224:225] op_sel:[1,0,0]
	v_pk_fma_f32 v[226:227], v[216:217], v[242:243], v[226:227] op_sel:[1,0,0]
	v_pk_fma_f32 v[228:229], v[216:217], v[244:245], v[228:229] op_sel:[1,0,0]
	v_pk_fma_f32 v[230:231], v[216:217], v[246:247], v[230:231] op_sel:[1,0,0]
	v_cvt_pk_f32_fp8_e32 v[240:241], v6
	v_cvt_pk_f32_fp8_sdwa v[242:243], v6 src0_sel:WORD_1
	v_cvt_pk_f32_fp8_e32 v[244:245], v7
	v_cvt_pk_f32_fp8_sdwa v[246:247], v7 src0_sel:WORD_1
	v_pk_fma_f32 v[232:233], v[216:217], v[232:233], 0 op_sel_hi:[0,1,0]
	v_pk_fma_f32 v[234:235], v[216:217], v[234:235], 0 op_sel_hi:[0,1,0]
	v_pk_fma_f32 v[236:237], v[216:217], v[236:237], 0 op_sel_hi:[0,1,0]
	v_pk_fma_f32 v[238:239], v[216:217], v[238:239], 0 op_sel_hi:[0,1,0]
	v_pk_fma_f32 v[232:233], v[216:217], v[240:241], v[232:233] op_sel:[1,0,0]
	v_pk_fma_f32 v[234:235], v[216:217], v[242:243], v[234:235] op_sel:[1,0,0]
	v_pk_fma_f32 v[236:237], v[216:217], v[244:245], v[236:237] op_sel:[1,0,0]
	v_pk_fma_f32 v[216:217], v[216:217], v[246:247], v[238:239] op_sel:[1,0,0]
	s_waitcnt vmcnt(30)
	v_cvt_pk_f32_fp8_e32 v[238:239], v8
	v_cvt_pk_f32_fp8_sdwa v[240:241], v8 src0_sel:WORD_1
	v_cvt_pk_f32_fp8_e32 v[242:243], v9
	v_cvt_pk_f32_fp8_sdwa v[244:245], v9 src0_sel:WORD_1
	v_pk_fma_f32 v[224:225], v[218:219], v[238:239], v[224:225] op_sel_hi:[0,1,1]
	v_pk_fma_f32 v[226:227], v[218:219], v[240:241], v[226:227] op_sel_hi:[0,1,1]
	v_pk_fma_f32 v[228:229], v[218:219], v[242:243], v[228:229] op_sel_hi:[0,1,1]
	v_pk_fma_f32 v[230:231], v[218:219], v[244:245], v[230:231] op_sel_hi:[0,1,1]
	v_cvt_pk_f32_fp8_e32 v[238:239], v10
	v_cvt_pk_f32_fp8_sdwa v[240:241], v10 src0_sel:WORD_1
	v_cvt_pk_f32_fp8_e32 v[242:243], v11
	v_cvt_pk_f32_fp8_sdwa v[244:245], v11 src0_sel:WORD_1
	v_pk_fma_f32 v[232:233], v[218:219], v[238:239], v[232:233] op_sel_hi:[0,1,1]
	v_pk_fma_f32 v[234:235], v[218:219], v[240:241], v[234:235] op_sel_hi:[0,1,1]
	v_pk_fma_f32 v[236:237], v[218:219], v[242:243], v[236:237] op_sel_hi:[0,1,1]
	v_pk_fma_f32 v[216:217], v[218:219], v[244:245], v[216:217] op_sel_hi:[0,1,1]
	v_mov_b32_e32 v138, v219
	s_waitcnt vmcnt(29)
	v_cvt_pk_f32_fp8_e32 v[218:219], v12
	v_cvt_pk_f32_fp8_sdwa v[238:239], v12 src0_sel:WORD_1
	v_cvt_pk_f32_fp8_e32 v[240:241], v13
	v_cvt_pk_f32_fp8_sdwa v[242:243], v13 src0_sel:WORD_1
	v_pk_fma_f32 v[218:219], v[138:139], v[218:219], v[224:225] op_sel_hi:[0,1,1]
	v_pk_fma_f32 v[224:225], v[138:139], v[238:239], v[226:227] op_sel_hi:[0,1,1]
	v_pk_fma_f32 v[226:227], v[138:139], v[240:241], v[228:229] op_sel_hi:[0,1,1]
	v_pk_fma_f32 v[228:229], v[138:139], v[242:243], v[230:231] op_sel_hi:[0,1,1]
	v_cvt_pk_f32_fp8_e32 v[230:231], v14
	v_cvt_pk_f32_fp8_sdwa v[238:239], v14 src0_sel:WORD_1
	v_cvt_pk_f32_fp8_e32 v[240:241], v15
	v_cvt_pk_f32_fp8_sdwa v[242:243], v15 src0_sel:WORD_1
	v_pk_fma_f32 v[230:231], v[138:139], v[230:231], v[232:233] op_sel_hi:[0,1,1]
	v_pk_fma_f32 v[232:233], v[138:139], v[238:239], v[234:235] op_sel_hi:[0,1,1]
	v_pk_fma_f32 v[234:235], v[138:139], v[240:241], v[236:237] op_sel_hi:[0,1,1]
	v_pk_fma_f32 v[216:217], v[138:139], v[242:243], v[216:217] op_sel_hi:[0,1,1]
	s_waitcnt vmcnt(28)
	v_cvt_pk_f32_fp8_e32 v[236:237], v16
	v_cvt_pk_f32_fp8_sdwa v[238:239], v16 src0_sel:WORD_1
	v_cvt_pk_f32_fp8_e32 v[240:241], v17
	v_cvt_pk_f32_fp8_sdwa v[242:243], v17 src0_sel:WORD_1
	s_waitcnt lgkmcnt(2)
	v_pk_fma_f32 v[218:219], v[220:221], v[236:237], v[218:219] op_sel_hi:[0,1,1]
	v_pk_fma_f32 v[224:225], v[220:221], v[238:239], v[224:225] op_sel_hi:[0,1,1]
	v_pk_fma_f32 v[226:227], v[220:221], v[240:241], v[226:227] op_sel_hi:[0,1,1]
	v_pk_fma_f32 v[228:229], v[220:221], v[242:243], v[228:229] op_sel_hi:[0,1,1]
	v_cvt_pk_f32_fp8_e32 v[236:237], v18
	v_cvt_pk_f32_fp8_sdwa v[238:239], v18 src0_sel:WORD_1
	v_cvt_pk_f32_fp8_e32 v[240:241], v19
	v_cvt_pk_f32_fp8_sdwa v[242:243], v19 src0_sel:WORD_1
	v_pk_fma_f32 v[230:231], v[220:221], v[236:237], v[230:231] op_sel_hi:[0,1,1]
	v_pk_fma_f32 v[232:233], v[220:221], v[238:239], v[232:233] op_sel_hi:[0,1,1]
	v_pk_fma_f32 v[234:235], v[220:221], v[240:241], v[234:235] op_sel_hi:[0,1,1]
	v_pk_fma_f32 v[216:217], v[220:221], v[242:243], v[216:217] op_sel_hi:[0,1,1]
	s_waitcnt vmcnt(27)
	v_cvt_pk_f32_fp8_e32 v[236:237], v20
	v_cvt_pk_f32_fp8_sdwa v[238:239], v20 src0_sel:WORD_1
	v_cvt_pk_f32_fp8_e32 v[240:241], v21
	v_cvt_pk_f32_fp8_sdwa v[242:243], v21 src0_sel:WORD_1
	v_pk_fma_f32 v[218:219], v[220:221], v[236:237], v[218:219] op_sel:[1,0,0]
	v_pk_fma_f32 v[224:225], v[220:221], v[238:239], v[224:225] op_sel:[1,0,0]
	v_pk_fma_f32 v[226:227], v[220:221], v[240:241], v[226:227] op_sel:[1,0,0]
	v_pk_fma_f32 v[228:229], v[220:221], v[242:243], v[228:229] op_sel:[1,0,0]
	v_cvt_pk_f32_fp8_e32 v[236:237], v22
	v_cvt_pk_f32_fp8_sdwa v[238:239], v22 src0_sel:WORD_1
	v_cvt_pk_f32_fp8_e32 v[240:241], v23
	v_cvt_pk_f32_fp8_sdwa v[242:243], v23 src0_sel:WORD_1
	v_pk_fma_f32 v[230:231], v[220:221], v[236:237], v[230:231] op_sel:[1,0,0]
	v_pk_fma_f32 v[232:233], v[220:221], v[238:239], v[232:233] op_sel:[1,0,0]
	v_pk_fma_f32 v[234:235], v[220:221], v[240:241], v[234:235] op_sel:[1,0,0]
	v_pk_fma_f32 v[216:217], v[220:221], v[242:243], v[216:217] op_sel:[1,0,0]
	s_waitcnt vmcnt(26)
	v_cvt_pk_f32_fp8_e32 v[220:221], v24
	v_cvt_pk_f32_fp8_sdwa v[236:237], v24 src0_sel:WORD_1
	v_cvt_pk_f32_fp8_e32 v[238:239], v25
	v_cvt_pk_f32_fp8_sdwa v[240:241], v25 src0_sel:WORD_1
	v_pk_fma_f32 v[218:219], v[222:223], v[220:221], v[218:219] op_sel_hi:[0,1,1]
	v_pk_fma_f32 v[220:221], v[222:223], v[236:237], v[224:225] op_sel_hi:[0,1,1]
	v_pk_fma_f32 v[224:225], v[222:223], v[238:239], v[226:227] op_sel_hi:[0,1,1]
	v_pk_fma_f32 v[226:227], v[222:223], v[240:241], v[228:229] op_sel_hi:[0,1,1]
	v_cvt_pk_f32_fp8_e32 v[228:229], v26
	v_cvt_pk_f32_fp8_sdwa v[236:237], v26 src0_sel:WORD_1
	v_cvt_pk_f32_fp8_e32 v[238:239], v27
	v_cvt_pk_f32_fp8_sdwa v[240:241], v27 src0_sel:WORD_1
	v_pk_fma_f32 v[228:229], v[222:223], v[228:229], v[230:231] op_sel_hi:[0,1,1]
	v_pk_fma_f32 v[230:231], v[222:223], v[236:237], v[232:233] op_sel_hi:[0,1,1]
	v_pk_fma_f32 v[232:233], v[222:223], v[238:239], v[234:235] op_sel_hi:[0,1,1]
	v_pk_fma_f32 v[216:217], v[222:223], v[240:241], v[216:217] op_sel_hi:[0,1,1]
	v_mov_b32_e32 v138, v223
	s_waitcnt vmcnt(25)
	v_cvt_pk_f32_fp8_e32 v[222:223], v28
	v_cvt_pk_f32_fp8_sdwa v[234:235], v28 src0_sel:WORD_1
	v_cvt_pk_f32_fp8_e32 v[236:237], v29
	v_cvt_pk_f32_fp8_sdwa v[238:239], v29 src0_sel:WORD_1
	v_pk_fma_f32 v[218:219], v[138:139], v[222:223], v[218:219] op_sel_hi:[0,1,1]
	v_pk_fma_f32 v[220:221], v[138:139], v[234:235], v[220:221] op_sel_hi:[0,1,1]
	v_pk_fma_f32 v[222:223], v[138:139], v[236:237], v[224:225] op_sel_hi:[0,1,1]
	v_pk_fma_f32 v[224:225], v[138:139], v[238:239], v[226:227] op_sel_hi:[0,1,1]
	v_cvt_pk_f32_fp8_e32 v[226:227], v30
	v_cvt_pk_f32_fp8_sdwa v[234:235], v30 src0_sel:WORD_1
	v_cvt_pk_f32_fp8_e32 v[236:237], v31
	v_cvt_pk_f32_fp8_sdwa v[238:239], v31 src0_sel:WORD_1
	v_pk_fma_f32 v[226:227], v[138:139], v[226:227], v[228:229] op_sel_hi:[0,1,1]
	v_pk_fma_f32 v[228:229], v[138:139], v[234:235], v[230:231] op_sel_hi:[0,1,1]
	v_pk_fma_f32 v[230:231], v[138:139], v[236:237], v[232:233] op_sel_hi:[0,1,1]
	v_pk_fma_f32 v[216:217], v[138:139], v[238:239], v[216:217] op_sel_hi:[0,1,1]
	s_waitcnt vmcnt(24)
	v_cvt_pk_f32_fp8_e32 v[232:233], v32
	v_cvt_pk_f32_fp8_sdwa v[234:235], v32 src0_sel:WORD_1
	v_cvt_pk_f32_fp8_e32 v[236:237], v33
	v_cvt_pk_f32_fp8_sdwa v[238:239], v33 src0_sel:WORD_1
	s_waitcnt lgkmcnt(1)
	v_pk_fma_f32 v[218:219], v[132:133], v[232:233], v[218:219] op_sel_hi:[0,1,1]
	v_pk_fma_f32 v[220:221], v[132:133], v[234:235], v[220:221] op_sel_hi:[0,1,1]
	v_pk_fma_f32 v[222:223], v[132:133], v[236:237], v[222:223] op_sel_hi:[0,1,1]
	v_pk_fma_f32 v[224:225], v[132:133], v[238:239], v[224:225] op_sel_hi:[0,1,1]
	v_cvt_pk_f32_fp8_e32 v[232:233], v34
	v_cvt_pk_f32_fp8_sdwa v[234:235], v34 src0_sel:WORD_1
	v_cvt_pk_f32_fp8_e32 v[236:237], v35
	v_cvt_pk_f32_fp8_sdwa v[238:239], v35 src0_sel:WORD_1
	v_pk_fma_f32 v[226:227], v[132:133], v[232:233], v[226:227] op_sel_hi:[0,1,1]
	v_pk_fma_f32 v[228:229], v[132:133], v[234:235], v[228:229] op_sel_hi:[0,1,1]
	v_pk_fma_f32 v[230:231], v[132:133], v[236:237], v[230:231] op_sel_hi:[0,1,1]
	v_pk_fma_f32 v[216:217], v[132:133], v[238:239], v[216:217] op_sel_hi:[0,1,1]
	s_waitcnt vmcnt(23)
	v_cvt_pk_f32_fp8_e32 v[232:233], v36
	v_cvt_pk_f32_fp8_sdwa v[234:235], v36 src0_sel:WORD_1
	v_cvt_pk_f32_fp8_e32 v[236:237], v37
	v_cvt_pk_f32_fp8_sdwa v[238:239], v37 src0_sel:WORD_1
	v_pk_fma_f32 v[218:219], v[132:133], v[232:233], v[218:219] op_sel:[1,0,0]
	v_pk_fma_f32 v[220:221], v[132:133], v[234:235], v[220:221] op_sel:[1,0,0]
	v_pk_fma_f32 v[222:223], v[132:133], v[236:237], v[222:223] op_sel:[1,0,0]
	v_pk_fma_f32 v[224:225], v[132:133], v[238:239], v[224:225] op_sel:[1,0,0]
	v_cvt_pk_f32_fp8_e32 v[232:233], v38
	v_cvt_pk_f32_fp8_sdwa v[234:235], v38 src0_sel:WORD_1
	v_cvt_pk_f32_fp8_e32 v[236:237], v39
	v_cvt_pk_f32_fp8_sdwa v[238:239], v39 src0_sel:WORD_1
	v_pk_fma_f32 v[226:227], v[132:133], v[232:233], v[226:227] op_sel:[1,0,0]
	v_pk_fma_f32 v[228:229], v[132:133], v[234:235], v[228:229] op_sel:[1,0,0]
	v_pk_fma_f32 v[230:231], v[132:133], v[236:237], v[230:231] op_sel:[1,0,0]
	v_pk_fma_f32 v[132:133], v[132:133], v[238:239], v[216:217] op_sel:[1,0,0]
	s_waitcnt vmcnt(22)
	v_cvt_pk_f32_fp8_e32 v[216:217], v40
	v_cvt_pk_f32_fp8_sdwa v[232:233], v40 src0_sel:WORD_1
	v_cvt_pk_f32_fp8_e32 v[234:235], v41
	v_cvt_pk_f32_fp8_sdwa v[236:237], v41 src0_sel:WORD_1
	v_pk_fma_f32 v[216:217], v[134:135], v[216:217], v[218:219] op_sel_hi:[0,1,1]
	v_pk_fma_f32 v[218:219], v[134:135], v[232:233], v[220:221] op_sel_hi:[0,1,1]
	v_pk_fma_f32 v[220:221], v[134:135], v[234:235], v[222:223] op_sel_hi:[0,1,1]
	v_pk_fma_f32 v[222:223], v[134:135], v[236:237], v[224:225] op_sel_hi:[0,1,1]
	v_cvt_pk_f32_fp8_e32 v[224:225], v42
	v_cvt_pk_f32_fp8_sdwa v[232:233], v42 src0_sel:WORD_1
	v_cvt_pk_f32_fp8_e32 v[234:235], v43
	v_cvt_pk_f32_fp8_sdwa v[236:237], v43 src0_sel:WORD_1
	v_pk_fma_f32 v[224:225], v[134:135], v[224:225], v[226:227] op_sel_hi:[0,1,1]
	v_pk_fma_f32 v[226:227], v[134:135], v[232:233], v[228:229] op_sel_hi:[0,1,1]
	v_pk_fma_f32 v[228:229], v[134:135], v[234:235], v[230:231] op_sel_hi:[0,1,1]
	v_pk_fma_f32 v[132:133], v[134:135], v[236:237], v[132:133] op_sel_hi:[0,1,1]
	s_waitcnt vmcnt(21)
	v_cvt_pk_f32_fp8_e32 v[230:231], v44
	v_cvt_pk_f32_fp8_sdwa v[232:233], v44 src0_sel:WORD_1
	v_cvt_pk_f32_fp8_e32 v[234:235], v45
	v_cvt_pk_f32_fp8_sdwa v[236:237], v45 src0_sel:WORD_1
	v_mov_b32_e32 v134, v135
	v_pk_fma_f32 v[216:217], v[134:135], v[230:231], v[216:217] op_sel_hi:[0,1,1]
	v_pk_fma_f32 v[218:219], v[134:135], v[232:233], v[218:219] op_sel_hi:[0,1,1]
	v_pk_fma_f32 v[220:221], v[134:135], v[234:235], v[220:221] op_sel_hi:[0,1,1]
	v_pk_fma_f32 v[222:223], v[134:135], v[236:237], v[222:223] op_sel_hi:[0,1,1]
	v_cvt_pk_f32_fp8_e32 v[230:231], v46
	v_cvt_pk_f32_fp8_sdwa v[232:233], v46 src0_sel:WORD_1
	v_cvt_pk_f32_fp8_e32 v[234:235], v47
	v_cvt_pk_f32_fp8_sdwa v[236:237], v47 src0_sel:WORD_1
	v_pk_fma_f32 v[224:225], v[134:135], v[230:231], v[224:225] op_sel_hi:[0,1,1]
	v_pk_fma_f32 v[226:227], v[134:135], v[232:233], v[226:227] op_sel_hi:[0,1,1]
	v_pk_fma_f32 v[228:229], v[134:135], v[234:235], v[228:229] op_sel_hi:[0,1,1]
	v_pk_fma_f32 v[132:133], v[134:135], v[236:237], v[132:133] op_sel_hi:[0,1,1]
	s_waitcnt vmcnt(20)
	v_cvt_pk_f32_fp8_e32 v[134:135], v48
	v_cvt_pk_f32_fp8_sdwa v[230:231], v48 src0_sel:WORD_1
	v_cvt_pk_f32_fp8_e32 v[232:233], v49
	v_cvt_pk_f32_fp8_sdwa v[234:235], v49 src0_sel:WORD_1
	s_waitcnt lgkmcnt(0)
	v_pk_fma_f32 v[134:135], v[128:129], v[134:135], v[216:217] op_sel_hi:[0,1,1]
	v_pk_fma_f32 v[216:217], v[128:129], v[230:231], v[218:219] op_sel_hi:[0,1,1]
	v_pk_fma_f32 v[218:219], v[128:129], v[232:233], v[220:221] op_sel_hi:[0,1,1]
	v_pk_fma_f32 v[220:221], v[128:129], v[234:235], v[222:223] op_sel_hi:[0,1,1]
	v_cvt_pk_f32_fp8_e32 v[222:223], v50
	v_cvt_pk_f32_fp8_sdwa v[230:231], v50 src0_sel:WORD_1
	v_cvt_pk_f32_fp8_e32 v[232:233], v51
	v_cvt_pk_f32_fp8_sdwa v[234:235], v51 src0_sel:WORD_1
	v_pk_fma_f32 v[222:223], v[128:129], v[222:223], v[224:225] op_sel_hi:[0,1,1]
	v_pk_fma_f32 v[224:225], v[128:129], v[230:231], v[226:227] op_sel_hi:[0,1,1]
	v_pk_fma_f32 v[226:227], v[128:129], v[232:233], v[228:229] op_sel_hi:[0,1,1]
	v_pk_fma_f32 v[132:133], v[128:129], v[234:235], v[132:133] op_sel_hi:[0,1,1]
	s_waitcnt vmcnt(19)
	v_cvt_pk_f32_fp8_e32 v[228:229], v52
	v_cvt_pk_f32_fp8_sdwa v[230:231], v52 src0_sel:WORD_1
	v_cvt_pk_f32_fp8_e32 v[232:233], v53
	v_cvt_pk_f32_fp8_sdwa v[234:235], v53 src0_sel:WORD_1
	v_pk_fma_f32 v[134:135], v[128:129], v[228:229], v[134:135] op_sel:[1,0,0]
	v_pk_fma_f32 v[216:217], v[128:129], v[230:231], v[216:217] op_sel:[1,0,0]
	v_pk_fma_f32 v[218:219], v[128:129], v[232:233], v[218:219] op_sel:[1,0,0]
	v_pk_fma_f32 v[220:221], v[128:129], v[234:235], v[220:221] op_sel:[1,0,0]
	v_cvt_pk_f32_fp8_e32 v[228:229], v54
	v_cvt_pk_f32_fp8_sdwa v[230:231], v54 src0_sel:WORD_1
	v_cvt_pk_f32_fp8_e32 v[232:233], v55
	v_cvt_pk_f32_fp8_sdwa v[234:235], v55 src0_sel:WORD_1
	v_pk_fma_f32 v[222:223], v[128:129], v[228:229], v[222:223] op_sel:[1,0,0]
	v_pk_fma_f32 v[224:225], v[128:129], v[230:231], v[224:225] op_sel:[1,0,0]
	v_pk_fma_f32 v[226:227], v[128:129], v[232:233], v[226:227] op_sel:[1,0,0]
	v_pk_fma_f32 v[128:129], v[128:129], v[234:235], v[132:133] op_sel:[1,0,0]
	s_waitcnt vmcnt(18)
	v_cvt_pk_f32_fp8_e32 v[132:133], v56
	v_cvt_pk_f32_fp8_sdwa v[228:229], v56 src0_sel:WORD_1
	v_cvt_pk_f32_fp8_e32 v[230:231], v57
	v_cvt_pk_f32_fp8_sdwa v[232:233], v57 src0_sel:WORD_1
	v_pk_fma_f32 v[132:133], v[130:131], v[132:133], v[134:135] op_sel_hi:[0,1,1]
	v_pk_fma_f32 v[134:135], v[130:131], v[228:229], v[216:217] op_sel_hi:[0,1,1]
	v_pk_fma_f32 v[216:217], v[130:131], v[230:231], v[218:219] op_sel_hi:[0,1,1]
	v_pk_fma_f32 v[218:219], v[130:131], v[232:233], v[220:221] op_sel_hi:[0,1,1]
	v_cvt_pk_f32_fp8_e32 v[220:221], v58
	v_cvt_pk_f32_fp8_sdwa v[228:229], v58 src0_sel:WORD_1
	v_cvt_pk_f32_fp8_e32 v[230:231], v59
	v_cvt_pk_f32_fp8_sdwa v[232:233], v59 src0_sel:WORD_1
	v_pk_fma_f32 v[220:221], v[130:131], v[220:221], v[222:223] op_sel_hi:[0,1,1]
	v_pk_fma_f32 v[222:223], v[130:131], v[228:229], v[224:225] op_sel_hi:[0,1,1]
	s_waitcnt vmcnt(17)
	s_and_b32 s101, s1, 3
	v_lshl_add_u32 v253, s101, 8, v252
	ds_read_b32 v210, v253
	ds_read_b32 v211, v253 offset:1024
	v_cvt_pk_f32_fp8_sdwa v[228:229], v60 src0_sel:WORD_1
	v_pk_fma_f32 v[224:225], v[130:131], v[230:231], v[226:227] op_sel_hi:[0,1,1]
	v_cvt_pk_f32_fp8_e32 v[226:227], v60
	v_cvt_pk_f32_fp8_e32 v[230:231], v61
	v_pk_fma_f32 v[128:129], v[130:131], v[232:233], v[128:129] op_sel_hi:[0,1,1]
	v_mov_b32_e32 v130, v131
	v_cvt_pk_f32_fp8_sdwa v[232:233], v61 src0_sel:WORD_1
	v_pk_fma_f32 v[134:135], v[130:131], v[228:229], v[134:135] op_sel_hi:[0,1,1]
	v_cvt_pk_f32_fp8_sdwa v[228:229], v62 src0_sel:WORD_1
	v_pk_fma_f32 v[132:133], v[130:131], v[226:227], v[132:133] op_sel_hi:[0,1,1]
	v_pk_fma_f32 v[216:217], v[130:131], v[230:231], v[216:217] op_sel_hi:[0,1,1]
	v_cvt_pk_f32_fp8_e32 v[226:227], v62
	v_cvt_pk_f32_fp8_e32 v[230:231], v63
	v_pk_fma_f32 v[218:219], v[130:131], v[232:233], v[218:219] op_sel_hi:[0,1,1]
	v_cvt_pk_f32_fp8_sdwa v[232:233], v63 src0_sel:WORD_1
	v_pk_fma_f32 v[222:223], v[130:131], v[228:229], v[222:223] op_sel_hi:[0,1,1]
	v_pk_fma_f32 v[220:221], v[130:131], v[226:227], v[220:221] op_sel_hi:[0,1,1]
	v_pk_fma_f32 v[224:225], v[130:131], v[230:231], v[224:225] op_sel_hi:[0,1,1]
	v_pk_fma_f32 v[128:129], v[130:131], v[232:233], v[128:129] op_sel_hi:[0,1,1]
	v_permlane32_swap_b32 v134, v222
	v_permlane32_swap_b32 v135, v223
	v_permlane32_swap_b32 v132, v220
	v_permlane32_swap_b32 v133, v221
	v_permlane32_swap_b32 v216, v224
	v_permlane32_swap_b32 v217, v225
	v_permlane32_swap_b32 v218, v128
	v_permlane32_swap_b32 v219, v129
	v_pk_add_f32 v[130:131], v[132:133], v[220:221]
	v_pk_add_f32 v[132:133], v[134:135], v[222:223]
	v_pk_add_f32 v[134:135], v[216:217], v[224:225]
	v_pk_add_f32 v[128:129], v[218:219], v[128:129]
	s_nop 1
	v_permlane16_swap_b32 v130, v134
	v_permlane16_swap_b32 v131, v135
	v_permlane16_swap_b32 v132, v128
	v_permlane16_swap_b32 v133, v129
	v_pk_add_f32 v[130:131], v[130:131], v[134:135]
	v_pk_add_f32 v[132:133], v[132:133], v[128:129]
	s_cmp_lg_u32 s1, 0
	v_cndmask_b32_e64 v128, v130, v132, s[12:13]
	v_cndmask_b32_e64 v129, v131, v133, s[12:13]
	ds_bpermute_b32 v128, v206, v128
	ds_bpermute_b32 v129, v206, v129
	v_lshlrev_b32_e32 v138, 2, v214
	s_cbranch_scc1 .LBB0_936
	global_load_dwordx2 v[178:179], v138, s[46:47]
	global_load_dwordx2 v[180:181], v138, s[48:49]
